# diff attention loop: K/V tile row addresses = scalar (row*6144) + per-lane part computed once per call; three 64-bit adds per tile instead of the 64-bit multiply-adds
# baseline (speedup 1.0000x reference)
; __device__ __forceinline__ int tid_opaque() { int t = threadIdx.x; asm volatile("" : "+v"(t)); return t; }
; template <int DQK, int DK1, int LDQ, int LDK, int LDKR, int LDV, int NQL, int SDEPTH>
; __device__ __forceinline__ void attn_core(const AttnArgs& a, char* lds, f32x16 (&o)[4]) {
;     constexpr int KP = DQK * 2, SHM_K = 64 * KP, SHM_V = 64 * 128 * 2, KCH = DQK / 64, CPR = DQK / 8, ND0 = DQK / 16;
;     const int tid = tid_opaque(), wid = tid >> 6, lane = tid & 63, r32 = lane & 31, hi = lane >> 5;
;     char* V_lds = lds; char* K_lds = lds + 2 * SHM_V;
;     float* wsf = (float*)(lds + 2 * SHM_V + 2 * SHM_K) + wid * 64; float* li_l = wsf; float* al_l = wsf + 32;
;     float m_reg = -1e30f, l_reg = 0.f;
; #pragma unroll
;     for (int d = 0; d < 4; ++d)
; #pragma unroll
;         for (int r = 0; r < 16; ++r) o[d][r] = 0.f;
;     constexpr int NQR = ND0 - NQL;
;     bf16x8 qr[NQR];
;     char* QL = lds + 2 * SHM_V + 2 * SHM_K + 2048 + tid * 16;
;     { const bf16_t* Qw = a.Q + (long)(wid * 32 + r32) * LDQ + hi * 8;
; #pragma unroll
;       for (int d0 = 0; d0 < NQR; ++d0) qr[d0] = *(const bf16x8*)(Qw + d0 * 16);
; #pragma unroll
;       for (int d0 = NQR; d0 < ND0; ++d0) *(bf16x8*)(QL + (d0 - NQR) * 8192) = *(const bf16x8*)(Qw + d0 * 16); }
;     const int sr = tid >> 4, sc = (tid & 15) * 8, vst0 = v_st(sr, sc), vst1 = v_st(32 + sr, sc);
;     const int vb0 = (int)(uintptr_t)V_lds + v_rd_base(lane);
;     const bf16_t* kptr[KCH]; int kld[KCH], kwo[KCH];
; #pragma unroll
;     for (int c = 0; c < KCH; ++c) { const int idx = tid + c * 512, kr_ = idx / CPR, kc = (idx % CPR) * 8;
;         if (kc < DK1) { kptr[c] = a.Kn + (long)kr_ * LDK + kc; kld[c] = LDK; } else { kptr[c] = a.Kr + (long)kr_ * LDKR + (kc - DK1); kld[c] = LDKR; }
;         kwo[c] = kr_ * KP + ((kc * 2) ^ ((kr_ & 7) << 4)); }
;     struct { bf16x8 vs0, vs1, ks[KCH]; } sr_[SDEPTH];
;     int kb[4];
; #pragma unroll
;     for (int m = 0; m < 4; ++m) kb[m] = r32 * KP + ((m * 32 + hi * 16) ^ ((r32 & 7) << 4));
;     ...
;     f32x16 pA0, pA1, pB0, pB1; float mnA, mnB, alA, alB; bf16x8 pa0, pa1, pa2, pa3; const int NT = a.NT;
;     constexpr int SE = 0, SO = SDEPTH - 1;
;     SLOAD(SE, 0); asm volatile("s_waitcnt vmcnt(0)" ::: "memory"); SWRITE(0, SE); __syncthreads();
;     QKT(pA0, pA1, K_lds); partialSM(pA0, pA1, m_reg, mnA, alA, a.C, a.thr);
.LBB0_170:
	v_mov_b32_e32 v14, v159
	s_xor_b64 s[94:95], s[14:15], -1
	s_lshl_b64 s[14:15], s[12:13], 1
	s_add_u32 s12, s87, s14
	v_ashrrev_i32_e32 v0, 31, v14
	v_lshrrev_b32_e32 v0, 29, v0
	s_addc_u32 s13, s68, s15
	v_add_u32_e32 v0, v14, v0
	s_add_u32 s14, s28, s14
	v_ashrrev_i32_e32 v16, 3, v0
	v_and_b32_e32 v0, -8, v0
	s_addc_u32 s15, s29, s15
	v_sub_u32_e32 v17, v14, v0
	v_ashrrev_i32_e32 v164, 4, v14
	v_lshlrev_b32_e32 v0, 3, v17
	v_mov_b64_e32 v[2:3], s[14:15]
	v_mad_i64_i32 v[2:3], s[14:15], v16, s9, v[2:3]
	v_ashrrev_i32_e32 v1, 31, v0
	v_ashrrev_i32_e32 v165, 31, v164
	v_lshlrev_b32_e32 v15, 3, v14
	v_lshl_add_u64 v[166:167], v[0:1], 1, v[2:3]
	v_lshl_add_u64 v[0:1], v[164:165], 0, s[18:19]
	v_mov_b64_e32 v[50:51], s[20:21]
	v_and_b32_e32 v4, 0x78, v15
	v_mad_u64_u32 v[2:3], s[14:15], v0, s9, v[50:51]
	v_mad_i32_i24 v3, v1, s9, v3
	v_lshlrev_b32_e32 v48, 1, v4
	v_mov_b32_e32 v49, v97
	v_lshl_add_u64 v[168:169], v[164:165], 0, 32
	v_lshl_add_u64 v[0:1], v[2:3], 0, v[48:49]
	v_lshl_add_u64 v[2:3], v[168:169], 0, s[18:19]
	v_mad_u64_u32 v[4:5], s[14:15], v2, s9, v[50:51]
	v_mad_i32_i24 v5, v3, s9, v5
	v_lshl_add_u64 v[4:5], v[4:5], 0, v[48:49]
	global_load_dwordx4 v[0:3], v[0:1], off
	s_nop 0
	global_load_dwordx4 v[4:7], v[4:5], off
	v_ashrrev_i32_e32 v12, 1, v14
	v_lshl_add_u64 v[8:9], v[166:167], 0, s[22:23]
	v_bfi_b32 v18, s33, v12, v14
	v_mov_b64_e32 v[12:13], s[12:13]
	global_load_dwordx4 v[8:11], v[8:9], off
	v_mad_i64_i32 v[12:13], s[12:13], v18, s9, v[12:13]
	v_lshrrev_b32_e32 v18, 1, v14
	v_and_b32_e32 v96, 16, v18
	v_lshl_add_u64 v[12:13], v[12:13], 0, v[96:97]
	global_load_dwordx4 v[110:113], v[12:13], off
	global_load_dwordx4 v[106:109], v[12:13], off offset:32
	global_load_dwordx4 v[102:105], v[12:13], off offset:64
	global_load_dwordx4 v[98:101], v[12:13], off offset:96
	v_and_b32_e32 v18, 0xfffff0, v164
	v_lshlrev_b32_e32 v19, 1, v164
	v_lshrrev_b32_e32 v20, 1, v164
	v_and_b32_e32 v21, 3, v164
	v_add_u32_e32 v22, 32, v164
	v_and_or_b32 v18, v19, 8, v18
	v_and_or_b32 v19, v20, 4, v21
	v_and_b32_e32 v20, 0xfffff0, v22
	v_lshlrev_b32_e32 v21, 1, v22
	v_bfe_u32 v15, v15, 5, 2
	v_lshrrev_b32_e32 v18, 1, v18
	v_and_or_b32 v20, v21, 8, v20
	v_and_b32_e32 v68, 31, v14
	v_lshlrev_b32_e32 v52, 4, v14
	v_or_b32_e32 v12, v18, v15
	v_lshrrev_b32_e32 v13, 1, v20
	v_lshlrev_b32_e32 v53, 7, v68
	v_and_b32_e32 v54, 0x70, v52
	v_and_b32_e32 v23, 48, v52
	v_lshlrev_b32_e32 v19, 6, v19
	v_lshlrev_b32_e32 v12, 9, v12
	v_or_b32_e32 v13, v13, v15
	v_bitop3_b32 v22, v96, v53, v54 bitop3:0xde
	v_lshlrev_b32_e32 v18, 7, v16
	v_bitop3_b32 v15, v16, v17, 7 bitop3:0x6c
	v_lshlrev_b32_e32 v13, 9, v13
	v_or3_b32 v12, v12, v19, v23
	v_lshl_add_u32 v15, v15, 4, v18
	v_or3_b32 v13, v13, v19, v23
	v_add_u32_e32 v181, 0, v12
	v_add_u32_e32 v186, 0, v22
	v_add_u32_e32 v182, 0, v15
	v_add_u32_e32 v184, 0, v13
	s_waitcnt vmcnt(0)
	v_and_b32_e32 v69, 63, v14
	v_lshl_add_u64 v[64:65], v[164:165], 0, s[88:89]
	v_mad_u64_u32 v[66:67], s[12:13], v64, s9, v[50:51]
	v_mad_i32_i24 v67, v65, s9, v67
	v_lshl_add_u64 v[60:61], v[166:167], 0, s[78:79]
	v_lshl_add_u64 v[64:65], v[66:67], 0, v[48:49]
	s_cmp_lg_u32 0, -1
	s_cselect_b32 s14, 0, 0
	s_waitcnt vmcnt(0)
	ds_write_b128 v181, v[0:3]
	s_waitcnt vmcnt(5)
	ds_write_b128 v184, v[4:7]
	s_waitcnt vmcnt(4)
	ds_write_b128 v182, v[8:11] offset:32768
	s_waitcnt lgkmcnt(0)
	s_barrier
	ds_read_b128 v[0:3], v186 offset:32768
	ds_read_b128 v[4:7], v186 offset:36864
	s_waitcnt vmcnt(3) lgkmcnt(1)
	v_mfma_f32_32x32x16_bf16 v[32:47], v[0:3], v[110:113], 0
	v_or_b32_e32 v0, 32, v96
	v_bitop3_b32 v0, v0, v53, v54 bitop3:0xde
	v_add_u32_e32 v188, 0, v0
	ds_read_b128 v[0:3], v188 offset:32768
	v_and_b32_e32 v8, 0x3fffffc0, v14
	v_lshl_add_u32 v161, v8, 2, 0
	v_lshlrev_b32_e32 v8, 3, v69
	s_waitcnt lgkmcnt(1)
	v_mfma_f32_32x32x16_bf16 v[16:31], v[4:7], v[110:113], 0
	ds_read_b128 v[4:7], v188 offset:36864
	s_mov_b32 s37, s36
	s_mov_b32 s38, s36
	s_mov_b32 s39, s36
	s_mov_b32 s40, s36
	s_mov_b32 s41, s36
	s_mov_b32 s42, s36
	s_waitcnt vmcnt(2) lgkmcnt(1)
	v_mfma_f32_32x32x16_bf16 v[32:47], v[0:3], v[106:109], v[32:47]
	v_or_b32_e32 v0, 64, v96
	v_bitop3_b32 v0, v0, v53, v54 bitop3:0xde
	v_add_u32_e32 v190, 0, v0
	ds_read_b128 v[0:3], v190 offset:32768
	s_mov_b32 s43, s36
	s_mov_b32 s44, s36
	s_mov_b32 s45, s36
	s_waitcnt lgkmcnt(1)
	v_mfma_f32_32x32x16_bf16 v[16:31], v[4:7], v[106:109], v[16:31]
	v_and_b32_e32 v4, 0xc0, v52
	v_lshlrev_b32_e32 v5, 1, v14
	v_and_or_b32 v4, v8, 24, v4
	v_and_b32_e32 v5, 32, v5
	v_and_b32_e32 v6, 0x100, v8
	v_or3_b32 v70, v4, v5, v6
	ds_read_b128 v[4:7], v190 offset:36864
	s_waitcnt vmcnt(1) lgkmcnt(1)
	v_mfma_f32_32x32x16_bf16 v[32:47], v[0:3], v[102:105], v[32:47]
	v_or_b32_e32 v0, 0x60, v96
	v_bitop3_b32 v0, v0, v53, v54 bitop3:0xde
	v_add_u32_e32 v192, 0, v0
	ds_read_b128 v[0:3], v192 offset:32768
	ds_read_b128 v[52:55], v192 offset:36864
	s_mov_b32 s46, s36
	s_mov_b32 s47, s36
	s_waitcnt lgkmcnt(2)
	v_mfma_f32_32x32x16_bf16 v[16:31], v[4:7], v[102:105], v[16:31]
	s_mov_b32 s48, s36
	s_mov_b32 s49, s36
	s_mov_b32 s50, s36
	s_mov_b32 s51, s36
	v_add_u32_e32 v180, s14, v70
	v_lshl_add_u64 v[170:171], s[20:21], 0, v[48:49]
	v_mad_u64_u32 v[248:249], vcc, v164, s9, v[170:171]
	v_mad_u64_u32 v[250:251], vcc, v168, s9, v[170:171]
	s_mov_b32 s52, 4
	s_waitcnt vmcnt(0) lgkmcnt(1)
	v_mfma_f32_32x32x16_bf16 v[32:47], v[0:3], v[98:101], v[32:47]
	v_mov_b64_e32 v[0:1], s[36:37]
	v_mov_b64_e32 v[14:15], s[50:51]
	v_mov_b64_e32 v[2:3], s[38:39]
	v_mov_b64_e32 v[4:5], s[40:41]
	v_mov_b64_e32 v[6:7], s[42:43]
	v_mov_b64_e32 v[8:9], s[44:45]
	v_mov_b64_e32 v[10:11], s[46:47]
	s_waitcnt lgkmcnt(0)
; #define SLOAD(i, j) do { const long rb_ = KROW(j); sr_[i].vs0 = *(const bf16x8*)(a.V + (rb_ + sr) * LDV + sc); sr_[i].vs1 = *(const bf16x8*)(a.V + (rb_ + 32 + sr) * LDV + sc); \
;     _Pragma("unroll") for (int c_ = 0; c_ < KCH; ++c_) sr_[i].ks[c_] = *(const bf16x8*)(kptr[c_] + rb_ * kld[c_]); } while (0)
; #define SWRITE(b, i) do { *(bf16x8*)(V_lds + (b) * SHM_V + vst0) = sr_[i].vs0; *(bf16x8*)(V_lds + (b) * SHM_V + vst1) = sr_[i].vs1; \
;     _Pragma("unroll") for (int c_ = 0; c_ < KCH; ++c_) *(bf16x8*)(K_lds + (b) * SHM_K + kwo[c_]) = sr_[i].ks[c_]; } while (0)
; __device__ __forceinline__ void partialSM(f32x16& p0, f32x16& p1, float& m_reg, float& mn, float& alpha, const float C, const float thr) {
;     float pmax = p0[0];
; #pragma unroll
;     for (int r = 1; r < 16; ++r) pmax = fmaxf(pmax, p0[r]);
; #pragma unroll
;     for (int r = 0; r < 16; ++r) pmax = fmaxf(pmax, p1[r]);
;     { auto rr = __builtin_amdgcn_permlane32_swap(__float_as_uint(pmax), __float_as_uint(pmax), false, false);
;       pmax = fmaxf(__uint_as_float(rr[0]), __uint_as_float(rr[1])); }
;     if (__builtin_expect(__all(pmax - m_reg <= thr), 1)) { mn = m_reg; alpha = 1.f; }
;     else { mn = fmaxf(m_reg, pmax); alpha = __builtin_amdgcn_exp2f((m_reg - mn) * C); m_reg = mn; }
;     const float mnC = -mn * C;
; #pragma unroll
;     for (int r = 0; r < 16; ++r) p0[r] = fmaf(p0[r], C, mnC);
; #pragma unroll
;     for (int r = 0; r < 16; ++r) p1[r] = fmaf(p1[r], C, mnC);
; #pragma unroll
;     for (int r = 0; r < 16; ++r) p0[r] = __builtin_amdgcn_exp2f(p0[r]);
; template <int DQK, int DK1, int LDQ, int LDK, int LDKR, int LDV, int NQL, int SDEPTH>
; __device__ __forceinline__ void attn_core(const AttnArgs& a, char* lds, f32x16 (&o)[4]) {
;     ...
;     SLOAD(SE, 0); asm volatile("s_waitcnt vmcnt(0)" ::: "memory"); SWRITE(0, SE); __syncthreads();
;     QKT(pA0, pA1, K_lds); partialSM(pA0, pA1, m_reg, mnA, alA, a.C, a.thr);
;     SLOAD(SO, 1); if (SDEPTH == 2 && 2 < NT) SLOAD(SE, 2);
;     SWRITE(1, SO); __syncthreads();
	v_mfma_f32_32x32x16_bf16 v[16:31], v[52:55], v[98:101], v[16:31]
	s_nop 2
	v_max_f32_e32 v52, v33, v33
	v_max_f32_e32 v53, v32, v32
	v_max_f32_e32 v52, v53, v52
	v_max3_f32 v52, v52, v34, v35
	v_max3_f32 v52, v52, v36, v37
	v_max3_f32 v52, v52, v38, v39
	v_max3_f32 v52, v52, v40, v41
	v_max3_f32 v52, v52, v42, v43
	v_max3_f32 v52, v52, v44, v45
	v_max3_f32 v52, v52, v46, v47
	v_max3_f32 v52, v52, v16, v17
	v_max3_f32 v71, v52, v18, v19
	v_lshl_add_u64 v[52:53], v[164:165], 0, s[24:25]
	v_mad_u64_u32 v[54:55], s[12:13], v52, s9, v[50:51]
	v_mad_i32_i24 v55, v53, s9, v55
	v_lshl_add_u64 v[52:53], v[54:55], 0, v[48:49]
	v_lshl_add_u64 v[54:55], v[168:169], 0, s[24:25]
	v_mad_u64_u32 v[56:57], s[12:13], v54, s9, v[50:51]
	v_mad_i32_i24 v57, v55, s9, v57
	v_lshl_add_u64 v[56:57], v[56:57], 0, v[48:49]
	global_load_dwordx4 v[52:55], v[52:53], off
	s_nop 0
	global_load_dwordx4 v[56:59], v[56:57], off
	v_mov_b64_e32 v[12:13], s[48:49]
	global_load_dwordx4 v[60:63], v[60:61], off
	v_lshl_add_u32 v177, v68, 2, v161
	global_load_dwordx4 v[114:117], v[64:65], off
	v_lshl_add_u64 v[64:65], v[168:169], 0, s[88:89]
	v_mad_u64_u32 v[50:51], s[12:13], v64, s9, v[50:51]
	v_mad_i32_i24 v51, v65, s9, v51
	v_lshl_add_u64 v[50:51], v[50:51], 0, v[48:49]
	v_lshl_add_u64 v[64:65], v[166:167], 0, s[90:91]
	global_load_dwordx4 v[118:121], v[50:51], off
	global_load_dwordx4 v[122:125], v[64:65], off
	v_max3_f32 v50, v71, v20, v21
	v_max3_f32 v50, v50, v22, v23
	v_max3_f32 v50, v50, v24, v25
	v_max3_f32 v50, v50, v26, v27
	v_max3_f32 v50, v50, v28, v29
	v_max3_f32 v50, v50, v30, v31
	v_mov_b32_e32 v51, v50
	s_nop 1
	v_permlane32_swap_b32_e32 v50, v51
	v_max_f32_e32 v51, v51, v51
	v_max_f32_e32 v50, v50, v50
	v_max_f32_e32 v50, v50, v51
	v_add_f32_e32 v51, 0x7149f2ca, v50
	v_max_f32_e32 v50, 0xf149f2ca, v50
	v_cmp_ge_f32_e32 vcc, s76, v51
	v_sub_f32_e32 v51, 0xf149f2ca, v50
	v_mul_f32_e32 v51, 0x3e38aa3b, v51
	v_exp_f32_e32 v51, v51
	s_cmp_eq_u64 vcc, exec
	s_cselect_b64 vcc, -1, 0
	v_cndmask_b32_e32 v142, v50, v193, vcc
	v_mul_f32_e32 v50, 0xbe38aa3b, v142
	v_cndmask_b32_e64 v194, v51, 1.0, vcc
	v_mov_b32_e32 v51, v50
	v_fmamk_f32 v32, v32, 0x3e38aa3b, v50
	v_fmamk_f32 v33, v33, 0x3e38aa3b, v50
	v_fmamk_f32 v34, v34, 0x3e38aa3b, v50
	v_fmamk_f32 v35, v35, 0x3e38aa3b, v50
	v_fmamk_f32 v36, v36, 0x3e38aa3b, v50
	v_fmamk_f32 v37, v37, 0x3e38aa3b, v50
	v_fmamk_f32 v38, v38, 0x3e38aa3b, v50
	v_fmamk_f32 v39, v39, 0x3e38aa3b, v50
	v_fmamk_f32 v40, v40, 0x3e38aa3b, v50
	v_fmamk_f32 v41, v41, 0x3e38aa3b, v50
	v_fmamk_f32 v42, v42, 0x3e38aa3b, v50
	v_fmamk_f32 v43, v43, 0x3e38aa3b, v50
	v_fmamk_f32 v44, v44, 0x3e38aa3b, v50
	v_fmamk_f32 v45, v45, 0x3e38aa3b, v50
	v_fmamk_f32 v46, v46, 0x3e38aa3b, v50
	v_fmac_f32_e32 v51, 0x3e38aa3b, v47
	v_exp_f32_e32 v217, v32
	v_exp_f32_e32 v219, v33
	v_exp_f32_e32 v208, v34
	v_exp_f32_e32 v218, v35
	v_exp_f32_e32 v153, v36
	v_exp_f32_e32 v216, v37
	v_exp_f32_e32 v152, v38
	v_exp_f32_e32 v202, v39
	v_exp_f32_e32 v149, v40
	v_exp_f32_e32 v151, v41
	v_exp_f32_e32 v147, v42
	v_exp_f32_e32 v150, v43
	v_exp_f32_e32 v145, v44
	v_exp_f32_e32 v148, v45
	v_exp_f32_e32 v144, v46
	v_exp_f32_e32 v146, v51
	v_pk_fma_f32 v[132:133], v[30:31], s[8:9], v[50:51] op_sel_hi:[1,0,0]
	v_pk_fma_f32 v[134:135], v[28:29], s[8:9], v[50:51] op_sel_hi:[1,0,0]
	v_pk_fma_f32 v[140:141], v[26:27], s[8:9], v[50:51] op_sel_hi:[1,0,0]
	v_pk_fma_f32 v[126:127], v[24:25], s[8:9], v[50:51] op_sel_hi:[1,0,0]
	v_pk_fma_f32 v[128:129], v[22:23], s[8:9], v[50:51] op_sel_hi:[1,0,0]
	v_pk_fma_f32 v[130:131], v[20:21], s[8:9], v[50:51] op_sel_hi:[1,0,0]
	v_pk_fma_f32 v[136:137], v[18:19], s[8:9], v[50:51] op_sel_hi:[1,0,0]
	v_pk_fma_f32 v[138:139], v[16:17], s[8:9], v[50:51] op_sel_hi:[1,0,0]
	s_waitcnt vmcnt(5)
	ds_write_b128 v181, v[52:55] offset:16384
	s_waitcnt vmcnt(4)
	ds_write_b128 v184, v[56:59] offset:16384
	s_waitcnt vmcnt(3)
	ds_write_b128 v182, v[60:63] offset:40960
	s_addk_i32 s14, 0x4000
	v_mov_b64_e32 v[30:31], v[14:15]
	v_mov_b64_e32 v[46:47], v[14:15]
	v_mov_b64_e32 v[62:63], v[14:15]
	v_cmp_gt_u32_e64 s[12:13], 32, v69
	v_add_u32_e32 v179, s14, v70
	v_mov_b32_e32 v178, 0
	v_mov_b64_e32 v[28:29], v[12:13]
	v_mov_b64_e32 v[26:27], v[10:11]
	v_mov_b64_e32 v[24:25], v[8:9]
	v_mov_b64_e32 v[22:23], v[6:7]
	v_mov_b64_e32 v[20:21], v[4:5]
	v_mov_b64_e32 v[18:19], v[2:3]
	v_mov_b64_e32 v[16:17], v[0:1]
	v_mov_b64_e32 v[44:45], v[12:13]
	v_mov_b64_e32 v[42:43], v[10:11]
	v_mov_b64_e32 v[40:41], v[8:9]
	v_mov_b64_e32 v[38:39], v[6:7]
	v_mov_b64_e32 v[36:37], v[4:5]
	v_mov_b64_e32 v[34:35], v[2:3]
	v_mov_b64_e32 v[32:33], v[0:1]
	v_mov_b64_e32 v[60:61], v[12:13]
	v_mov_b64_e32 v[58:59], v[10:11]
	v_mov_b64_e32 v[56:57], v[8:9]
	v_mov_b64_e32 v[54:55], v[6:7]
	v_mov_b64_e32 v[52:53], v[4:5]
	v_mov_b64_e32 v[50:51], v[2:3]
	v_mov_b64_e32 v[48:49], v[0:1]
	s_waitcnt lgkmcnt(0)
	s_barrier
; #define SBAR() __builtin_amdgcn_sched_barrier(0)
; #define SLOAD(i, j) do { const long rb_ = KROW(j); sr_[i].vs0 = *(const bf16x8*)(a.V + (rb_ + sr) * LDV + sc); sr_[i].vs1 = *(const bf16x8*)(a.V + (rb_ + 32 + sr) * LDV + sc); \
;     _Pragma("unroll") for (int c_ = 0; c_ < KCH; ++c_) sr_[i].ks[c_] = *(const bf16x8*)(kptr[c_] + rb_ * kld[c_]); } while (0)
; #define SWRITE(b, i) do { *(bf16x8*)(V_lds + (b) * SHM_V + vst0) = sr_[i].vs0; *(bf16x8*)(V_lds + (b) * SHM_V + vst1) = sr_[i].vs1; \
;     _Pragma("unroll") for (int c_ = 0; c_ < KCH; ++c_) *(bf16x8*)(K_lds + (b) * SHM_K + kwo[c_]) = sr_[i].ks[c_]; } while (0)
; __device__ __forceinline__ void finishSM(f32x16& p0, f32x16& p1, float alpha, float& l_reg, bf16x8& pa0, bf16x8& pa1, bf16x8& pa2, bf16x8& pa3) {
; #pragma unroll
;     for (int r = 0; r < 16; ++r) p1[r] = __builtin_amdgcn_exp2f(p1[r]);
;     float ps = 0;
; #pragma unroll
;     for (int r = 0; r < 16; ++r) ps += p0[r];
; #pragma unroll
;     for (int r = 0; r < 16; ++r) ps += p1[r];
;     { auto rr = __builtin_amdgcn_permlane32_swap(__float_as_uint(ps), __float_as_uint(ps), false, false);
;       ps = __uint_as_float(rr[0]) + __uint_as_float(rr[1]); }
;     l_reg = l_reg * alpha + ps;
;     ...
;     PK4(p0, 0, pa0); PK4(p0, 8, pa1); PK4(p1, 0, pa2); PK4(p1, 8, pa3);
; template <int DQK, int DK1, int LDQ, int LDK, int LDKR, int LDV, int NQL, int SDEPTH>
; __device__ __forceinline__ void attn_core(const AttnArgs& a, char* lds, f32x16 (&o)[4]) {
;     ...
;     f32x16 pA0, pA1, pB0, pB1; float mnA, mnB, alA, alB; bf16x8 pa0, pa1, pa2, pa3; const int NT = a.NT;
;     constexpr int SE = 0, SO = SDEPTH - 1;
;     SLOAD(SE, 0); asm volatile("s_waitcnt vmcnt(0)" ::: "memory"); SWRITE(0, SE); __syncthreads();
;     QKT(pA0, pA1, K_lds); partialSM(pA0, pA1, m_reg, mnA, alA, a.C, a.thr);
;     SLOAD(SO, 1); if (SDEPTH == 2 && 2 < NT) SLOAD(SE, 2);
;     SWRITE(1, SO); __syncthreads();
;     for (int j = 1; j + 1 < NT; j += 2) {
;         SBAR(); QKT(pB0, pB1, K_lds + SHM_K);
;         finishSM(pA0, pA1, alA, l_reg, pa0, pa1, pa2, pa3); SBAR();
;         SLOAD(SO, j + SDEPTH); SBAR();
;         pv_d0(o, vb0, pa0, pa1, pa2, pa3); partialSM(pB0, pB1, m_reg, mnB, alB, a.C, a.thr);
.LBB0_171:
	s_add_i32 s37, s52, -3
	ds_read_b128 v[64:67], v186 offset:40960
	ds_read_b128 v[68:71], v186 offset:45056
	v_exp_f32_e32 v143, v138
	v_add_f32_e32 v138, 0, v217
	v_add_f32_e32 v138, v219, v138
	s_waitcnt lgkmcnt(1)
	v_mfma_f32_32x32x16_bf16 v[80:95], v[64:67], v[110:113], 0
	v_add_f32_e32 v138, v208, v138
	v_add_f32_e32 v138, v218, v138
	v_add_f32_e32 v138, v153, v138
	ds_read_b128 v[204:207], v188 offset:40960
	ds_read_b128 v[220:223], v188 offset:45056
	v_add_f32_e32 v138, v216, v138
	v_add_f32_e32 v138, v152, v138
	v_add_f32_e32 v138, v202, v138
	s_waitcnt lgkmcnt(2)
	v_mfma_f32_32x32x16_bf16 v[64:79], v[68:71], v[110:113], 0
	v_add_f32_e32 v138, v149, v138
	v_add_f32_e32 v138, v151, v138
	v_add_f32_e32 v138, v147, v138
	v_add_f32_e32 v138, v150, v138
	v_add_f32_e32 v138, v145, v138
	v_exp_f32_e32 v191, v139
	v_add_f32_e32 v138, v148, v138
	s_waitcnt lgkmcnt(1)
	v_mfma_f32_32x32x16_bf16 v[80:95], v[204:207], v[106:109], v[80:95]
	v_exp_f32_e32 v136, v136
	v_add_f32_e32 v138, v144, v138
	v_exp_f32_e32 v137, v137
	v_add_f32_e32 v138, v146, v138
	v_exp_f32_e32 v130, v130
	v_add_f32_e32 v138, v143, v138
	v_exp_f32_e32 v131, v131
	s_waitcnt lgkmcnt(0)
	v_mfma_f32_32x32x16_bf16 v[64:79], v[220:223], v[106:109], v[64:79]
	ds_read_b128 v[204:207], v190 offset:40960
	ds_read_b128 v[220:223], v190 offset:45056
	v_add_f32_e32 v138, v191, v138
	v_exp_f32_e32 v128, v128
	v_add_f32_e32 v138, v136, v138
	v_exp_f32_e32 v129, v129
	v_add_f32_e32 v138, v137, v138
	v_exp_f32_e32 v126, v126
	s_waitcnt lgkmcnt(1)
	v_mfma_f32_32x32x16_bf16 v[80:95], v[204:207], v[102:105], v[80:95]
	v_add_f32_e32 v138, v130, v138
	v_exp_f32_e32 v127, v127
	v_add_f32_e32 v138, v131, v138
	v_exp_f32_e32 v200, v140
	v_add_f32_e32 v138, v128, v138
	v_exp_f32_e32 v210, v141
	v_add_f32_e32 v138, v129, v138
	s_waitcnt lgkmcnt(0)
	v_mfma_f32_32x32x16_bf16 v[64:79], v[220:223], v[102:105], v[64:79]
	ds_read_b128 v[204:207], v192 offset:40960
	ds_read_b128 v[220:223], v192 offset:45056
	v_exp_f32_e32 v134, v134
	v_add_f32_e32 v138, v126, v138
	v_exp_f32_e32 v135, v135
	v_add_f32_e32 v138, v127, v138
	v_exp_f32_e32 v132, v132
	v_add_f32_e32 v138, v200, v138
	s_waitcnt lgkmcnt(1)
	v_mfma_f32_32x32x16_bf16 v[80:95], v[204:207], v[98:101], v[80:95]
	v_exp_f32_e32 v133, v133
	v_add_f32_e32 v138, v210, v138
	v_add_f32_e32 v138, v134, v138
	v_add_f32_e32 v138, v135, v138
	v_add_f32_e32 v138, v132, v138
	v_add_f32_e32 v196, v133, v138
	v_mov_b32_e32 v198, v196
	s_waitcnt lgkmcnt(0)
	v_mfma_f32_32x32x16_bf16 v[64:79], v[220:223], v[98:101], v[64:79]
	v_cvt_pk_bf16_f32 v138, v217, v219
	v_cvt_pk_bf16_f32 v139, v208, v218
	v_cvt_pk_bf16_f32 v140, v153, v216
	v_permlane32_swap_b32_e32 v196, v198
	v_cvt_pk_bf16_f32 v141, v152, v202
	v_permlane32_swap_b32_e32 v138, v140
	v_cvt_pk_bf16_f32 v204, v149, v151
	v_cvt_pk_bf16_f32 v205, v147, v150
	v_cvt_pk_bf16_f32 v206, v145, v148
	v_cvt_pk_bf16_f32 v207, v144, v146
	v_cvt_pk_bf16_f32 v144, v143, v191
	v_cvt_pk_bf16_f32 v145, v136, v137
	v_cvt_pk_bf16_f32 v146, v130, v131
	v_cvt_pk_bf16_f32 v147, v128, v129
	v_cvt_pk_bf16_f32 v148, v126, v127
	v_cvt_pk_bf16_f32 v149, v200, v210
	v_cvt_pk_bf16_f32 v150, v134, v135
	v_cvt_pk_bf16_f32 v151, v132, v133
	v_permlane32_swap_b32_e32 v139, v141
	v_permlane32_swap_b32_e32 v204, v206
	v_permlane32_swap_b32_e32 v205, v207
	v_permlane32_swap_b32_e32 v144, v146
	v_permlane32_swap_b32_e32 v145, v147
	v_permlane32_swap_b32_e32 v148, v150
	v_permlane32_swap_b32_e32 v149, v151
	s_cmp_lt_u32 s37, 30
	s_cselect_b32 s14, 0, 0xffffffe0
	s_cselect_b32 s15, s18, s86
	s_add_i32 s14, s14, s52
	s_lshl_b32 s14, s14, 6
	s_add_i32 s14, s14, s15
	s_sub_i32 s14, s14, 64
	s_mul_hi_i32 s39, s14, s9
	s_mul_i32 s38, s14, s9
	v_lshl_add_u64 v[128:129], s[38:39], 0, v[248:249]
	v_lshl_add_u64 v[132:133], s[38:39], 0, v[250:251]
	v_lshl_add_u64 v[134:135], s[38:39], 0, v[166:167]
	global_load_dwordx4 v[126:129], v[128:129], off
	s_nop 0
	global_load_dwordx4 v[130:133], v[132:133], off
	s_nop 0
	global_load_dwordx4 v[134:137], v[134:135], off
	ds_read_b64_tr_b16 v[216:217], v180 offset:0
	ds_read_b64_tr_b16 v[218:219], v180 offset:0x800
	ds_read_b64_tr_b16 v[220:221], v180 offset:0x1000
	ds_read_b64_tr_b16 v[222:223], v180 offset:0x1800
	ds_read_b64_tr_b16 v[224:225], v180 offset:0x2000
	ds_read_b64_tr_b16 v[226:227], v180 offset:0x2800
	ds_read_b64_tr_b16 v[228:229], v180 offset:0x3000
	ds_read_b64_tr_b16 v[230:231], v180 offset:0x3800
	s_waitcnt lgkmcnt(0)
	s_nop 0
	v_mfma_f32_32x32x16_bf16 v[48:63], v[138:141], v[216:219], v[48:63]
	ds_read_b64_tr_b16 v[216:217], v180 offset:0x200
	ds_read_b64_tr_b16 v[218:219], v180 offset:0xa00
	v_max_f32_e32 v238, v81, v81
	v_max_f32_e32 v239, v80, v80
	v_max_f32_e32 v238, v239, v238
	v_max3_f32 v238, v238, v82, v83
	v_max3_f32 v238, v238, v84, v85
	v_max3_f32 v238, v238, v86, v87
	v_mfma_f32_32x32x16_bf16 v[48:63], v[204:207], v[220:223], v[48:63]
	ds_read_b64_tr_b16 v[220:221], v180 offset:0x1200
	ds_read_b64_tr_b16 v[222:223], v180 offset:0x1a00
	v_max3_f32 v238, v238, v88, v89
	v_max3_f32 v238, v238, v90, v91
	v_max3_f32 v238, v238, v92, v93
	v_max3_f32 v238, v238, v94, v95
	v_max3_f32 v238, v238, v64, v65
	v_max3_f32 v238, v238, v66, v67
	v_mfma_f32_32x32x16_bf16 v[48:63], v[144:147], v[224:227], v[48:63]
	ds_read_b64_tr_b16 v[224:225], v180 offset:0x2200
	ds_read_b64_tr_b16 v[226:227], v180 offset:0x2a00
	v_max3_f32 v238, v238, v68, v69
	v_max3_f32 v238, v238, v70, v71
	v_max3_f32 v238, v238, v72, v73
	v_max3_f32 v238, v238, v74, v75
	v_max3_f32 v238, v238, v76, v77
	v_max3_f32 v238, v238, v78, v79
	v_mfma_f32_32x32x16_bf16 v[48:63], v[148:151], v[228:231], v[48:63]
	ds_read_b64_tr_b16 v[228:229], v180 offset:0x3200
	ds_read_b64_tr_b16 v[230:231], v180 offset:0x3a00
	v_mov_b32_e32 v239, v238
	s_nop 1
	v_permlane32_swap_b32_e32 v238, v239
	v_max_f32_e32 v239, v239, v239
	v_max_f32_e32 v238, v238, v238
	v_max_f32_e32 v238, v238, v239
	s_waitcnt lgkmcnt(0)
; #define SBAR() __builtin_amdgcn_sched_barrier(0)
; template <int OFF> __device__ __forceinline__ s16x4 tr_read(int vb) { s16x4 r; asm volatile("ds_read_b64_tr_b16 %0, %1 offset:%2" : "=&v"(r) : "v"(vb), "i"(OFF) : "memory"); return r; }
; template <int D0> __device__ __forceinline__ void pv_one(f32x16& od, int vb, bf16x8 pa0, bf16x8 pa1, bf16x8 pa2, bf16x8 pa3) {
;     const s16x4 l0 = tr_read<v_rd_off(D0, 0, 0)>(vb), h0 = tr_read<v_rd_off(D0, 0, 1)>(vb), l1 = tr_read<v_rd_off(D0, 1, 0)>(vb), h1 = tr_read<v_rd_off(D0, 1, 1)>(vb);
;     const s16x4 l2 = tr_read<v_rd_off(D0, 2, 0)>(vb), h2 = tr_read<v_rd_off(D0, 2, 1)>(vb), l3 = tr_read<v_rd_off(D0, 3, 0)>(vb), h3 = tr_read<v_rd_off(D0, 3, 1)>(vb);
;     asm volatile("s_waitcnt lgkmcnt(0)" ::: "memory"); SBAR();
;     ...
;     od = __builtin_amdgcn_mfma_f32_32x32x16_bf16(pa0, PK(l0, h0), od, 0, 0, 0);
;     od = __builtin_amdgcn_mfma_f32_32x32x16_bf16(pa1, PK(l1, h1), od, 0, 0, 0);
;     od = __builtin_amdgcn_mfma_f32_32x32x16_bf16(pa2, PK(l2, h2), od, 0, 0, 0);
;     od = __builtin_amdgcn_mfma_f32_32x32x16_bf16(pa3, PK(l3, h3), od, 0, 0, 0);
;     ...
; }
; __device__ __forceinline__ void pv_d0(f32x16* o, int vb, bf16x8 pa0, bf16x8 pa1, bf16x8 pa2, bf16x8 pa3) {
;     pv_one<0>(o[0], vb, pa0, pa1, pa2, pa3); pv_one<1>(o[1], vb, pa0, pa1, pa2, pa3); pv_one<2>(o[2], vb, pa0, pa1, pa2, pa3); pv_one<3>(o[3], vb, pa0, pa1, pa2, pa3);
; }
; __device__ __forceinline__ void partialSM(f32x16& p0, f32x16& p1, float& m_reg, float& mn, float& alpha, const float C, const float thr) {
;     float pmax = p0[0];
; #pragma unroll
;     for (int r = 1; r < 16; ++r) pmax = fmaxf(pmax, p0[r]);
; #pragma unroll
;     for (int r = 0; r < 16; ++r) pmax = fmaxf(pmax, p1[r]);
;     { auto rr = __builtin_amdgcn_permlane32_swap(__float_as_uint(pmax), __float_as_uint(pmax), false, false);
;       pmax = fmaxf(__uint_as_float(rr[0]), __uint_as_float(rr[1])); }
;     if (__builtin_expect(__all(pmax - m_reg <= thr), 1)) { mn = m_reg; alpha = 1.f; }
;     else { mn = fmaxf(m_reg, pmax); alpha = __builtin_amdgcn_exp2f((m_reg - mn) * C); m_reg = mn; }
;     const float mnC = -mn * C;
; #pragma unroll
;     for (int r = 0; r < 16; ++r) p0[r] = fmaf(p0[r], C, mnC);
; #pragma unroll
;     for (int r = 0; r < 16; ++r) p1[r] = fmaf(p1[r], C, mnC);
; #pragma unroll
;     for (int r = 0; r < 16; ++r) p0[r] = __builtin_amdgcn_exp2f(p0[r]);
; }
	v_mfma_f32_32x32x16_bf16 v[32:47], v[138:141], v[216:219], v[32:47]
	ds_read_b64_tr_b16 v[216:217], v180 offset:0x400
	ds_read_b64_tr_b16 v[218:219], v180 offset:0xc00
	v_sub_f32_e32 v239, v238, v142
	v_cmp_ge_f32_e32 vcc, s76, v239
	v_max_f32_e32 v239, v142, v142
	v_max_f32_e32 v238, v239, v238
	v_sub_f32_e32 v239, v142, v238
	v_mul_f32_e32 v239, 0x3e38aa3b, v239
	v_mfma_f32_32x32x16_bf16 v[32:47], v[204:207], v[220:223], v[32:47]
	ds_read_b64_tr_b16 v[220:221], v180 offset:0x1400
	ds_read_b64_tr_b16 v[222:223], v180 offset:0x1c00
	v_exp_f32_e32 v239, v239
	s_cmp_eq_u64 vcc, exec
	s_cselect_b64 s[14:15], -1, 0
	v_cndmask_b32_e64 v200, v239, 1.0, s[14:15]
	v_cmp_gt_f32_e32 vcc, 1.0, v200
	v_mfma_f32_32x32x16_bf16 v[32:47], v[144:147], v[224:227], v[32:47]
	ds_read_b64_tr_b16 v[224:225], v180 offset:0x2400
	ds_read_b64_tr_b16 v[226:227], v180 offset:0x2c00
	v_cndmask_b32_e64 v241, v238, v142, s[14:15]
	v_mul_f32_e32 v239, 0xbe38aa3b, v241
	v_fmamk_f32 v80, v80, 0x3e38aa3b, v239
	v_fmamk_f32 v81, v81, 0x3e38aa3b, v239
	v_mfma_f32_32x32x16_bf16 v[32:47], v[148:151], v[228:231], v[32:47]
	ds_read_b64_tr_b16 v[228:229], v180 offset:0x3400
	ds_read_b64_tr_b16 v[230:231], v180 offset:0x3c00
	v_fmamk_f32 v82, v82, 0x3e38aa3b, v239
	v_fmamk_f32 v83, v83, 0x3e38aa3b, v239
	v_fmamk_f32 v84, v84, 0x3e38aa3b, v239
	v_fmamk_f32 v85, v85, 0x3e38aa3b, v239
	s_waitcnt lgkmcnt(0)
	v_mfma_f32_32x32x16_bf16 v[16:31], v[138:141], v[216:219], v[16:31]
	ds_read_b64_tr_b16 v[216:217], v180 offset:0x600
	ds_read_b64_tr_b16 v[218:219], v180 offset:0xe00
	v_fmamk_f32 v86, v86, 0x3e38aa3b, v239
	v_fmamk_f32 v87, v87, 0x3e38aa3b, v239
	v_fmamk_f32 v88, v88, 0x3e38aa3b, v239
	v_fmamk_f32 v89, v89, 0x3e38aa3b, v239
	v_mfma_f32_32x32x16_bf16 v[16:31], v[204:207], v[220:223], v[16:31]
	ds_read_b64_tr_b16 v[220:221], v180 offset:0x1600
	ds_read_b64_tr_b16 v[222:223], v180 offset:0x1e00
	v_fmamk_f32 v90, v90, 0x3e38aa3b, v239
	v_fmamk_f32 v91, v91, 0x3e38aa3b, v239
	v_fmamk_f32 v92, v92, 0x3e38aa3b, v239
	v_fmamk_f32 v93, v93, 0x3e38aa3b, v239
	v_mfma_f32_32x32x16_bf16 v[16:31], v[144:147], v[224:227], v[16:31]
	ds_read_b64_tr_b16 v[224:225], v180 offset:0x2600
	ds_read_b64_tr_b16 v[226:227], v180 offset:0x2e00
	v_fmamk_f32 v94, v94, 0x3e38aa3b, v239
	v_fmamk_f32 v95, v95, 0x3e38aa3b, v239
	v_mfma_f32_32x32x16_bf16 v[16:31], v[148:151], v[228:231], v[16:31]
	ds_read_b64_tr_b16 v[228:229], v180 offset:0x3600
	ds_read_b64_tr_b16 v[230:231], v180 offset:0x3e00
	v_exp_f32_e32 v153, v81
	v_exp_f32_e32 v152, v83
	v_exp_f32_e32 v142, v88
	v_exp_f32_e32 v143, v90
	s_waitcnt lgkmcnt(0)
	v_mfma_f32_32x32x16_bf16 v[0:15], v[138:141], v[216:219], v[0:15]
	v_mfma_f32_32x32x16_bf16 v[0:15], v[204:207], v[220:223], v[0:15]
	v_exp_f32_e32 v138, v80
	v_mfma_f32_32x32x16_bf16 v[0:15], v[144:147], v[224:227], v[0:15]
	v_exp_f32_e32 v144, v92
	v_exp_f32_e32 v147, v93
	v_exp_f32_e32 v145, v94
	v_exp_f32_e32 v146, v95
	v_exp_f32_e32 v139, v82
	v_mfma_f32_32x32x16_bf16 v[0:15], v[148:151], v[228:231], v[0:15]
	v_exp_f32_e32 v140, v84
	v_exp_f32_e32 v141, v86
	s_barrier
	s_waitcnt vmcnt(5)
	ds_write_b128 v181, v[114:117]
	s_waitcnt vmcnt(4)
	ds_write_b128 v184, v[118:121]
	s_waitcnt vmcnt(3)
	ds_write_b128 v182, v[122:125] offset:32768
	s_cbranch_vccz .LBB0_175
	s_and_saveexec_b64 s[38:39], s[12:13]
	ds_write_b32 v177, v200 offset:49280
	s_or_b64 exec, exec, s[38:39]
	s_waitcnt lgkmcnt(0)
	v_add_u32_e32 v242, v161, v96
	ds_read_b128 v[244:247], v242 offset:49376
	ds_read_b128 v[148:151], v242 offset:49344
	ds_read_b128 v[204:207], v242 offset:49312
	ds_read_b128 v[216:219], v242 offset:49280
	s_waitcnt lgkmcnt(3)
	v_pk_mul_f32 v[60:61], v[60:61], v[244:245]
	s_waitcnt lgkmcnt(2)
	v_pk_mul_f32 v[56:57], v[56:57], v[148:149]
	s_waitcnt lgkmcnt(1)
	v_pk_mul_f32 v[52:53], v[52:53], v[204:205]
	v_pk_mul_f32 v[62:63], v[62:63], v[246:247]
	v_pk_mul_f32 v[58:59], v[58:59], v[150:151]
	v_pk_mul_f32 v[54:55], v[54:55], v[206:207]
	s_waitcnt lgkmcnt(0)
	v_pk_mul_f32 v[50:51], v[50:51], v[218:219]
	v_pk_mul_f32 v[48:49], v[48:49], v[216:217]
	v_pk_mul_f32 v[44:45], v[44:45], v[244:245]
	v_pk_mul_f32 v[40:41], v[40:41], v[148:149]
	v_pk_mul_f32 v[36:37], v[36:37], v[204:205]
	v_pk_mul_f32 v[46:47], v[46:47], v[246:247]
	v_pk_mul_f32 v[42:43], v[42:43], v[150:151]
	v_pk_mul_f32 v[38:39], v[38:39], v[206:207]
	v_pk_mul_f32 v[34:35], v[34:35], v[218:219]
	v_pk_mul_f32 v[32:33], v[32:33], v[216:217]
	v_pk_mul_f32 v[28:29], v[28:29], v[244:245]
	v_pk_mul_f32 v[24:25], v[24:25], v[148:149]
	v_pk_mul_f32 v[20:21], v[20:21], v[204:205]
	v_pk_mul_f32 v[30:31], v[30:31], v[246:247]
	v_pk_mul_f32 v[26:27], v[26:27], v[150:151]
	v_pk_mul_f32 v[22:23], v[22:23], v[206:207]
	v_pk_mul_f32 v[18:19], v[18:19], v[218:219]
	v_pk_mul_f32 v[16:17], v[16:17], v[216:217]
	v_pk_mul_f32 v[12:13], v[12:13], v[244:245]
	v_pk_mul_f32 v[8:9], v[8:9], v[148:149]
	v_pk_mul_f32 v[4:5], v[4:5], v[204:205]
	v_pk_mul_f32 v[14:15], v[14:15], v[246:247]
	v_pk_mul_f32 v[10:11], v[10:11], v[150:151]
	v_pk_mul_f32 v[6:7], v[6:7], v[206:207]
	v_pk_mul_f32 v[2:3], v[2:3], v[218:219]
	v_pk_mul_f32 v[0:1], v[0:1], v[216:217]
; __device__ __forceinline__ void partialSM(f32x16& p0, f32x16& p1, float& m_reg, float& mn, float& alpha, const float C, const float thr) {
;     ...
;     const float mnC = -mn * C;
; #pragma unroll
;     for (int r = 0; r < 16; ++r) p0[r] = fmaf(p0[r], C, mnC);
; #pragma unroll
;     for (int r = 0; r < 16; ++r) p1[r] = fmaf(p1[r], C, mnC);
; #pragma unroll
;     for (int r = 0; r < 16; ++r) p0[r] = __builtin_amdgcn_exp2f(p0[r]);
; }
; __device__ __forceinline__ void finishSM(f32x16& p0, f32x16& p1, float alpha, float& l_reg, bf16x8& pa0, bf16x8& pa1, bf16x8& pa2, bf16x8& pa3) {
; #pragma unroll
;     for (int r = 0; r < 16; ++r) p1[r] = __builtin_amdgcn_exp2f(p1[r]);
;     float ps = 0;
; #pragma unroll
;     for (int r = 0; r < 16; ++r) ps += p0[r];
; #pragma unroll
;     for (int r = 0; r < 16; ++r) ps += p1[r];
;     { auto rr = __builtin_amdgcn_permlane32_swap(__float_as_uint(ps), __float_as_uint(ps), false, false);
;       ps = __uint_as_float(rr[0]) + __uint_as_float(rr[1]); }
;     l_reg = l_reg * alpha + ps;
;     ...
;     PK4(p0, 0, pa0); PK4(p0, 8, pa1); PK4(p1, 0, pa2); PK4(p1, 8, pa3);
.LBB0_175:
	v_mov_b32_e32 v202, v241
	v_mul_f32_e32 v204, 0xbe38aa3b, v202
	v_exp_f32_e32 v151, v85
	v_exp_f32_e32 v150, v87
	v_exp_f32_e32 v149, v89
	v_exp_f32_e32 v148, v91
	v_fmamk_f32 v222, v64, 0x3e38aa3b, v204
	v_fmamk_f32 v223, v65, 0x3e38aa3b, v204
	v_fmamk_f32 v224, v66, 0x3e38aa3b, v204
	v_fmamk_f32 v225, v67, 0x3e38aa3b, v204
	v_fmamk_f32 v226, v68, 0x3e38aa3b, v204
	v_fmamk_f32 v208, v69, 0x3e38aa3b, v204
	v_fmamk_f32 v216, v70, 0x3e38aa3b, v204
	v_fmamk_f32 v217, v71, 0x3e38aa3b, v204
	v_fmamk_f32 v218, v72, 0x3e38aa3b, v204
	v_fmamk_f32 v219, v73, 0x3e38aa3b, v204
	v_fmamk_f32 v220, v74, 0x3e38aa3b, v204
	v_fmamk_f32 v221, v75, 0x3e38aa3b, v204
	v_fmamk_f32 v206, v76, 0x3e38aa3b, v204
	v_fmamk_f32 v227, v77, 0x3e38aa3b, v204
	v_fmamk_f32 v228, v78, 0x3e38aa3b, v204
	v_fmac_f32_e32 v204, 0x3e38aa3b, v79
	s_waitcnt lgkmcnt(0)
	s_barrier
	ds_read_b128 v[64:67], v186 offset:32768
	ds_read_b128 v[68:71], v186 offset:36864
	v_exp_f32_e32 v205, v223
	v_exp_f32_e32 v223, v204
	v_add_f32_e32 v204, 0, v138
	v_add_f32_e32 v204, v153, v204
	s_waitcnt lgkmcnt(1)
	v_mfma_f32_32x32x16_bf16 v[80:95], v[64:67], v[110:113], 0
	v_add_f32_e32 v204, v139, v204
	v_add_f32_e32 v204, v152, v204
	v_add_f32_e32 v204, v140, v204
	ds_read_b128 v[230:233], v188 offset:32768
	ds_read_b128 v[234:237], v188 offset:36864
	v_add_f32_e32 v204, v151, v204
	v_add_f32_e32 v204, v141, v204
	v_add_f32_e32 v204, v150, v204
	s_waitcnt lgkmcnt(2)
	v_mfma_f32_32x32x16_bf16 v[64:79], v[68:71], v[110:113], 0
	v_add_f32_e32 v204, v142, v204
	v_add_f32_e32 v204, v149, v204
	v_add_f32_e32 v204, v143, v204
	v_add_f32_e32 v204, v148, v204
	v_exp_f32_e32 v191, v222
	v_add_f32_e32 v204, v144, v204
	v_add_f32_e32 v204, v147, v204
	s_waitcnt lgkmcnt(1)
	v_mfma_f32_32x32x16_bf16 v[80:95], v[230:233], v[106:109], v[80:95]
	v_exp_f32_e32 v207, v224
	v_add_f32_e32 v204, v145, v204
	v_exp_f32_e32 v210, v225
	v_add_f32_e32 v204, v146, v204
	v_exp_f32_e32 v211, v226
	v_add_f32_e32 v204, v191, v204
	v_exp_f32_e32 v208, v208
	s_waitcnt lgkmcnt(0)
	v_mfma_f32_32x32x16_bf16 v[64:79], v[234:237], v[106:109], v[64:79]
	ds_read_b128 v[230:233], v190 offset:32768
	ds_read_b128 v[234:237], v190 offset:36864
	v_add_f32_e32 v204, v205, v204
	v_exp_f32_e32 v212, v216
	v_add_f32_e32 v204, v207, v204
	v_exp_f32_e32 v213, v217
	v_add_f32_e32 v204, v210, v204
	v_exp_f32_e32 v216, v218
	s_waitcnt lgkmcnt(1)
	v_mfma_f32_32x32x16_bf16 v[80:95], v[230:233], v[102:105], v[80:95]
	v_add_f32_e32 v204, v211, v204
	v_exp_f32_e32 v217, v219
	v_add_f32_e32 v204, v208, v204
	v_exp_f32_e32 v218, v220
	v_add_f32_e32 v204, v212, v204
	v_exp_f32_e32 v219, v221
	v_add_f32_e32 v204, v213, v204
	s_waitcnt lgkmcnt(0)
	v_mfma_f32_32x32x16_bf16 v[64:79], v[234:237], v[102:105], v[64:79]
	ds_read_b128 v[230:233], v192 offset:32768
	ds_read_b128 v[234:237], v192 offset:36864
	v_exp_f32_e32 v220, v206
	v_add_f32_e32 v204, v216, v204
	v_exp_f32_e32 v221, v227
	v_add_f32_e32 v204, v217, v204
	v_exp_f32_e32 v222, v228
	v_add_f32_e32 v204, v218, v204
	s_waitcnt lgkmcnt(1)
	v_mfma_f32_32x32x16_bf16 v[80:95], v[230:233], v[98:101], v[80:95]
	v_add_f32_e32 v204, v219, v204
	v_add_f32_e32 v204, v220, v204
	v_add_f32_e32 v204, v221, v204
	v_add_f32_e32 v204, v222, v204
	v_add_f32_e32 v204, v223, v204
	v_mov_b32_e32 v206, v204
	v_cvt_pk_bf16_f32 v138, v138, v153
	s_waitcnt lgkmcnt(0)
	v_mfma_f32_32x32x16_bf16 v[64:79], v[234:237], v[98:101], v[64:79]
	v_cvt_pk_bf16_f32 v139, v139, v152
	v_cvt_pk_bf16_f32 v140, v140, v151
	v_cvt_pk_bf16_f32 v141, v141, v150
	v_cvt_pk_bf16_f32 v142, v142, v149
	v_cvt_pk_bf16_f32 v143, v143, v148
	v_cvt_pk_bf16_f32 v144, v144, v147
	v_cvt_pk_bf16_f32 v145, v145, v146
	v_cvt_pk_bf16_f32 v146, v191, v205
	v_cvt_pk_bf16_f32 v147, v207, v210
	v_cvt_pk_bf16_f32 v148, v211, v208
	v_cvt_pk_bf16_f32 v149, v212, v213
	v_cvt_pk_bf16_f32 v150, v216, v217
	v_cvt_pk_bf16_f32 v151, v218, v219
	v_cvt_pk_bf16_f32 v152, v220, v221
	v_cvt_pk_bf16_f32 v153, v222, v223
	v_permlane32_swap_b32_e32 v204, v206
	v_permlane32_swap_b32_e32 v138, v140
	v_permlane32_swap_b32_e32 v139, v141
	v_permlane32_swap_b32_e32 v142, v144
	v_permlane32_swap_b32_e32 v143, v145
	v_permlane32_swap_b32_e32 v146, v148
	v_permlane32_swap_b32_e32 v147, v149
	v_permlane32_swap_b32_e32 v150, v152
	v_permlane32_swap_b32_e32 v151, v153
	s_cmp_gt_u32 s37, 32
	s_cbranch_scc1 .LBB0_177
	s_cmp_lt_u32 s37, 29
	s_cselect_b32 s14, 0, 0xffffffe0
	s_cselect_b32 s15, s18, s86
	s_add_i32 s14, s14, s52
	s_lshl_b32 s14, s14, 6
	s_add_i32 s14, s14, s15
	s_mul_hi_i32 s39, s14, s9
	s_mul_i32 s38, s14, s9
	v_lshl_add_u64 v[116:117], s[38:39], 0, v[248:249]
	v_lshl_add_u64 v[120:121], s[38:39], 0, v[250:251]
	v_lshl_add_u64 v[122:123], s[38:39], 0, v[166:167]
	global_load_dwordx4 v[114:117], v[116:117], off
	s_nop 0
	global_load_dwordx4 v[118:121], v[120:121], off
	s_nop 0
	global_load_dwordx4 v[122:125], v[122:123], off
